# Fourier stage-1 tile epilogue: the four twiddle loads issued ahead of the staging barrier, four row groups unrolled with counted vmcnt instead of a store drain per trip
# baseline (speedup 1.0000x reference)
.LBB0_456:
	s_and_b64 vcc, exec, s[0:1]
	s_cbranch_vccz .LBB0_451
	s_bfe_u32 s1, s3, 0x10001
	v_mov_b32_e32 v35, v138
	s_bfe_u32 s0, s3, 0x60002
	s_lshl_b32 s12, s1, 15
	v_readlane_b32 s16, v207, 45
	v_readlane_b32 s17, v207, 46
	v_ashrrev_i32_e32 v36, 3, v35
	s_add_u32 s16, s16, s12
	v_ashrrev_i32_e32 v37, 31, v36
	s_addc_u32 s17, s17, 0
	v_lshlrev_b64 v[0:1], 8, v[36:37]
	v_lshlrev_b32_e32 v2, 4, v35
	v_lshl_add_u64 v[0:1], s[16:17], 0, v[0:1]
	v_and_b32_e32 v134, 0x70, v2
	v_lshl_add_u64 v[4:5], v[0:1], 0, v[134:135]
	s_movk_i32 s16, 0x2000
	v_add_co_u32_e32 v8, vcc, s16, v4
	s_nop 1
	v_addc_co_u32_e32 v9, vcc, 0, v5, vcc
	v_add_co_u32_e32 v12, vcc, s66, v4
	s_barrier
	global_load_dwordx4 v[0:3], v[4:5], off
	v_addc_co_u32_e32 v13, vcc, 0, v5, vcc
	s_movk_i32 s16, 0x6000
	global_load_dwordx4 v[20:23], v[8:9], off
	v_add_co_u32_e32 v16, vcc, s16, v4
	global_load_dwordx4 v[24:27], v[12:13], off
	s_nop 0
	v_addc_co_u32_e32 v17, vcc, 0, v5, vcc
	global_load_dwordx4 v[28:31], v[16:17], off
	s_lshl_b32 s12, s3, 5
	s_and_b32 s12, s12, 0xffffe000
	s_or_b32 s12, s12, s0
	s_mul_hi_i32 s13, s12, 0xe00
	s_mulk_i32 s12, 0xe00
	v_readlane_b32 s20, v206, 43
	v_readlane_b32 s21, v206, 44
	s_add_u32 s18, s20, s12
	s_addc_u32 s13, s21, s13
	s_lshl_b32 s12, s3, 8
	s_and_b32 s12, s12, 0x100
	s_add_u32 s16, s18, s12
	s_addc_u32 s17, s13, 0
	v_lshlrev_b32_e32 v10, 3, v35
	v_ashrrev_i32_e32 v37, 4, v35
	v_mov_b64_e32 v[38:39], s[16:17]
	s_mov_b32 s13, 0x38000
	v_and_b32_e32 v64, 0x78, v10
	v_mad_i64_i32 v[6:7], s[16:17], v37, s13, v[38:39]
	v_lshlrev_b32_e32 v56, 1, v64
	v_mov_b32_e32 v57, v135
	v_lshl_add_u64 v[6:7], v[6:7], 0, v[56:57]
	global_load_dwordx4 v[40:43], v[6:7], off offset:512
	v_add_u32_e32 v65, 0x100, v35
	v_ashrrev_i32_e32 v60, 4, v65
	v_mad_i64_i32 v[6:7], s[16:17], v60, s13, v[38:39]
	v_add_u32_e32 v66, 0x200, v35
	v_lshl_add_u64 v[6:7], v[6:7], 0, v[56:57]
	v_ashrrev_i32_e32 v62, 4, v66
	global_load_dwordx4 v[44:47], v[6:7], off offset:512
	v_mad_i64_i32 v[6:7], s[16:17], v62, s13, v[38:39]
	v_add_u32_e32 v67, 0x300, v35
	v_lshl_add_u64 v[6:7], v[6:7], 0, v[56:57]
	v_ashrrev_i32_e32 v68, 4, v67
	global_load_dwordx4 v[48:51], v[6:7], off offset:512
	v_mad_i64_i32 v[6:7], s[16:17], v68, s13, v[38:39]
	v_lshl_add_u64 v[6:7], v[6:7], 0, v[56:57]
	global_load_dwordx4 v[52:55], v[6:7], off offset:512
	v_add_u32_e32 v37, 64, v37
	v_mad_i64_i32 v[58:59], s[16:17], v37, s13, v[38:39]
	v_add_u32_e32 v37, 64, v60
	v_mad_i64_i32 v[60:61], s[16:17], v37, s13, v[38:39]
	v_add_u32_e32 v37, 64, v62
	v_mad_i64_i32 v[62:63], s[16:17], v37, s13, v[38:39]
	v_add_u32_e32 v37, 64, v68
	v_mad_i64_i32 v[38:39], s[16:17], v37, s13, v[38:39]
	v_lshl_add_u64 v[58:59], v[58:59], 0, v[56:57]
	v_lshl_add_u64 v[60:61], v[60:61], 0, v[56:57]
	v_lshl_add_u64 v[62:63], v[62:63], 0, v[56:57]
	v_lshl_add_u64 v[56:57], v[38:39], 0, v[56:57]
	v_mad_u64_u32 v[38:39], s[16:17], v36, s67, v[134:135]
	v_ashrrev_i32_e32 v69, 7, v35
	global_load_dwordx4 v[4:7], v[4:5], off offset:128
	s_nop 0
	global_load_dwordx4 v[8:11], v[8:9], off offset:128
	s_nop 0
	global_load_dwordx4 v[12:15], v[12:13], off offset:128
	s_nop 0
	global_load_dwordx4 v[16:19], v[16:17], off offset:128
	s_waitcnt vmcnt(11)
	ds_write_b128 v38, v[0:3]
	s_waitcnt vmcnt(10)
	ds_write_b128 v38, v[20:23] offset:4608
	s_waitcnt vmcnt(9)
	ds_write_b128 v38, v[24:27] offset:9216
	s_waitcnt vmcnt(8)
	ds_write_b128 v38, v[28:31] offset:13824
	v_lshrrev_b32_e32 v2, 3, v35
	v_bitop3_b32 v0, v69, v35, 7 bitop3:0x78
	v_mul_u32_u24_e32 v1, 0x48, v64
	v_and_b32_e32 v36, 14, v2
	v_lshl_or_b32 v0, v0, 4, v36
	v_lshlrev_b32_e32 v37, 1, v1
	v_add_u32_e32 v39, v37, v0
	global_load_dwordx4 v[28:31], v[58:59], off offset:512
	global_load_dwordx4 v[24:27], v[60:61], off offset:512
	global_load_dwordx4 v[20:23], v[62:63], off offset:512
	global_load_dwordx4 v[0:3], v[56:57], off offset:512
	s_waitcnt vmcnt(11)
	ds_write_b16 v39, v40 offset:18432
	ds_write_b16_d16_hi v39, v40 offset:18576
	ds_write_b16 v39, v41 offset:18720
	ds_write_b16_d16_hi v39, v41 offset:18864
	ds_write_b16 v39, v42 offset:19008
	ds_write_b16_d16_hi v39, v42 offset:19152
	ds_write_b16 v39, v43 offset:19296
	ds_write_b16_d16_hi v39, v43 offset:19440
	v_ashrrev_i32_e32 v40, 7, v65
	v_bitop3_b32 v40, v40, v35, 7 bitop3:0x78
	v_lshl_or_b32 v40, v40, 4, v36
	v_add_u32_e32 v124, v37, v40
	v_ashrrev_i32_e32 v40, 7, v66
	v_bitop3_b32 v40, v40, v35, 7 bitop3:0x78
	v_lshl_or_b32 v40, v40, 4, v36
	v_add_u32_e32 v125, v37, v40
	v_ashrrev_i32_e32 v40, 7, v67
	v_bitop3_b32 v40, v40, v35, 7 bitop3:0x78
	v_lshl_or_b32 v36, v40, 4, v36
	v_add_u32_e32 v126, v37, v36
	v_and_b32_e32 v36, 15, v35
	v_and_b32_e32 v37, 63, v35
	v_lshl_or_b32 v40, v69, 6, v36
	v_and_b32_e32 v36, 48, v35
	v_bfe_u32 v117, v37, 3, 1
	v_mad_u64_u32 v[36:37], s[16:17], v40, s67, v[36:37]
	s_waitcnt vmcnt(10)
	ds_write_b16 v124, v44 offset:18432
	ds_write_b16_d16_hi v124, v44 offset:18576
	ds_write_b16 v124, v45 offset:18720
	ds_write_b16_d16_hi v124, v45 offset:18864
	ds_write_b16 v124, v46 offset:19008
	ds_write_b16_d16_hi v124, v46 offset:19152
	ds_write_b16 v124, v47 offset:19296
	ds_write_b16_d16_hi v124, v47 offset:19440
	s_waitcnt vmcnt(9)
	ds_write_b16 v125, v48 offset:18432
	ds_write_b16_d16_hi v125, v48 offset:18576
	ds_write_b16 v125, v49 offset:18720
	ds_write_b16_d16_hi v125, v49 offset:18864
	ds_write_b16 v125, v50 offset:19008
	ds_write_b16_d16_hi v125, v50 offset:19152
	ds_write_b16 v125, v51 offset:19296
	ds_write_b16_d16_hi v125, v51 offset:19440
	s_waitcnt vmcnt(8)
	ds_write_b16 v126, v52 offset:18432
	ds_write_b16_d16_hi v126, v52 offset:18576
	ds_write_b16 v126, v53 offset:18720
	ds_write_b16_d16_hi v126, v53 offset:18864
	ds_write_b16 v126, v54 offset:19008
	ds_write_b16_d16_hi v126, v54 offset:19152
	ds_write_b16 v126, v55 offset:19296
	ds_write_b16_d16_hi v126, v55 offset:19440
	s_waitcnt lgkmcnt(0)
	s_barrier
	v_and_b32_e32 v120, 0x4f, v35
	v_bfe_u32 v116, v35, 4, 2
	v_bfe_u32 v35, v35, 3, 3
	ds_read_b128 v[40:43], v36
	ds_read_b128 v[72:75], v36 offset:2304
	ds_read_b128 v[108:111], v36 offset:64
	ds_read_b128 v[88:91], v36 offset:4608
	ds_read_b128 v[104:107], v36 offset:6912
	v_bitop3_b32 v37, v35, v116, 1 bitop3:0x6c
	v_bitop3_b32 v48, v117, v116, 2 bitop3:0x36
	v_bitop3_b32 v56, v117, v116, 4 bitop3:0x36
	v_bitop3_b32 v64, v35, v116, 6 bitop3:0x36
	v_lshlrev_b32_e32 v37, 4, v37
	v_lshlrev_b32_e32 v48, 4, v48
	v_lshlrev_b32_e32 v56, 4, v56
	v_lshlrev_b32_e32 v64, 4, v64
	v_mad_u32_u24 v37, v120, s67, v37
	v_mad_u32_u24 v127, v120, s67, v48
	v_mad_u32_u24 v128, v120, s67, v56
	v_mad_u32_u24 v129, v120, s67, v64
	v_or_b32_e32 v121, 4, v116
	ds_read_b128 v[44:47], v37 offset:18432
	ds_read_b128 v[48:51], v127 offset:20736
	ds_read_b128 v[56:59], v128 offset:23040
	ds_read_b128 v[68:71], v129 offset:25344
	v_bitop3_b32 v112, v35, v121, 1 bitop3:0x6c
	v_lshlrev_b32_e32 v112, 4, v112
	v_mad_u32_u24 v134, v120, s67, v112
	v_bitop3_b32 v112, v117, v121, 2 bitop3:0x36
	v_bitop3_b32 v116, v117, v116, 4 bitop3:0x14
	v_bitop3_b32 v35, v35, v121, 6 bitop3:0x36
	v_lshlrev_b32_e32 v118, 4, v112
	v_lshlrev_b32_e32 v116, 4, v116
	v_lshlrev_b32_e32 v35, 4, v35
	v_mad_u32_u24 v136, v120, s67, v118
	v_mad_u32_u24 v137, v120, s67, v116
	v_mad_u32_u24 v35, v120, s67, v35
	s_waitcnt lgkmcnt(3)
	v_mfma_f32_16x16x32_bf16 v[76:79], v[72:75], v[44:47], 0
	ds_read_b128 v[112:115], v134 offset:18432
	ds_read_b128 v[116:119], v137 offset:23040
	ds_read_b128 v[120:123], v35 offset:25344
	v_mfma_f32_16x16x32_bf16 v[52:55], v[40:43], v[44:47], 0
	s_lshl_b32 s1, s1, 6
	s_lshl_b32 s16, s0, 1
	s_and_b32 s17, s3, 0xffffff00
	s_waitcnt lgkmcnt(5)
	v_mfma_f32_16x16x32_bf16 v[60:63], v[40:43], v[48:51], 0
	s_lshl_b32 s0, s0, 9
	v_readlane_b32 s18, v206, 55
	s_add_u32 s0, s18, s0
	s_waitcnt lgkmcnt(4)
	v_mfma_f32_16x16x32_bf16 v[64:67], v[40:43], v[56:59], 0
	v_readlane_b32 s18, v206, 56
	s_addc_u32 s18, s18, 0
	s_add_u32 s38, s0, s12
	s_waitcnt lgkmcnt(3)
	v_mfma_f32_16x16x32_bf16 v[40:43], v[40:43], v[68:71], 0
	s_addc_u32 s39, s18, 0
	s_mov_b32 s13, 0
	v_mfma_f32_16x16x32_bf16 v[80:83], v[72:75], v[48:51], 0
	v_mfma_f32_16x16x32_bf16 v[84:87], v[72:75], v[56:59], 0
	v_mfma_f32_16x16x32_bf16 v[72:75], v[72:75], v[68:71], 0
	v_mfma_f32_16x16x32_bf16 v[92:95], v[88:91], v[44:47], 0
	v_mfma_f32_16x16x32_bf16 v[96:99], v[88:91], v[48:51], 0
	v_mfma_f32_16x16x32_bf16 v[100:103], v[88:91], v[56:59], 0
	v_mfma_f32_16x16x32_bf16 v[88:91], v[88:91], v[68:71], 0
	v_mfma_f32_16x16x32_bf16 v[44:47], v[104:107], v[44:47], 0
	v_mfma_f32_16x16x32_bf16 v[48:51], v[104:107], v[48:51], 0
	v_mfma_f32_16x16x32_bf16 v[56:59], v[104:107], v[56:59], 0
	v_mfma_f32_16x16x32_bf16 v[68:71], v[104:107], v[68:71], 0
	ds_read_b128 v[104:107], v136 offset:20736
	s_waitcnt lgkmcnt(3)
	v_mfma_f32_16x16x32_bf16 v[52:55], v[108:111], v[112:115], v[52:55]
	s_waitcnt lgkmcnt(0)
	v_mfma_f32_16x16x32_bf16 v[60:63], v[108:111], v[104:107], v[60:63]
	v_mfma_f32_16x16x32_bf16 v[64:67], v[108:111], v[116:119], v[64:67]
	v_mfma_f32_16x16x32_bf16 v[40:43], v[108:111], v[120:123], v[40:43]
	ds_read_b128 v[108:111], v36 offset:2368
	s_waitcnt lgkmcnt(0)
	v_mfma_f32_16x16x32_bf16 v[76:79], v[108:111], v[112:115], v[76:79]
	v_mfma_f32_16x16x32_bf16 v[80:83], v[108:111], v[104:107], v[80:83]
	v_mfma_f32_16x16x32_bf16 v[84:87], v[108:111], v[116:119], v[84:87]
	v_mfma_f32_16x16x32_bf16 v[72:75], v[108:111], v[120:123], v[72:75]
	ds_read_b128 v[108:111], v36 offset:4672
	s_waitcnt lgkmcnt(0)
	v_mfma_f32_16x16x32_bf16 v[92:95], v[108:111], v[112:115], v[92:95]
	v_mfma_f32_16x16x32_bf16 v[96:99], v[108:111], v[104:107], v[96:99]
	v_mfma_f32_16x16x32_bf16 v[100:103], v[108:111], v[116:119], v[100:103]
	v_mfma_f32_16x16x32_bf16 v[88:91], v[108:111], v[120:123], v[88:91]
	ds_read_b128 v[108:111], v36 offset:6976
	s_waitcnt vmcnt(7)
	ds_write_b128 v38, v[4:7] offset:36864
	s_waitcnt vmcnt(6)
	ds_write_b128 v38, v[8:11] offset:41472
	s_waitcnt vmcnt(5)
	ds_write_b128 v38, v[12:15] offset:46080
	s_waitcnt vmcnt(4)
	ds_write_b128 v38, v[16:19] offset:50688
	s_waitcnt vmcnt(3)
	ds_write_b16 v39, v28 offset:55296
	ds_write_b16_d16_hi v39, v28 offset:55440
	ds_write_b16 v39, v29 offset:55584
	ds_write_b16_d16_hi v39, v29 offset:55728
	ds_write_b16 v39, v30 offset:55872
	ds_write_b16_d16_hi v39, v30 offset:56016
	ds_write_b16 v39, v31 offset:56160
	ds_write_b16_d16_hi v39, v31 offset:56304
	s_waitcnt vmcnt(2)
	ds_write_b16 v124, v24 offset:55296
	ds_write_b16_d16_hi v124, v24 offset:55440
	ds_write_b16 v124, v25 offset:55584
	ds_write_b16_d16_hi v124, v25 offset:55728
	ds_write_b16 v124, v26 offset:55872
	ds_write_b16_d16_hi v124, v26 offset:56016
	ds_write_b16 v124, v27 offset:56160
	ds_write_b16_d16_hi v124, v27 offset:56304
	s_waitcnt vmcnt(1)
	ds_write_b16 v125, v20 offset:55296
	ds_write_b16_d16_hi v125, v20 offset:55440
	ds_write_b16 v125, v21 offset:55584
	ds_write_b16_d16_hi v125, v21 offset:55728
	ds_write_b16 v125, v22 offset:55872
	ds_write_b16_d16_hi v125, v22 offset:56016
	ds_write_b16 v125, v23 offset:56160
	ds_write_b16_d16_hi v125, v23 offset:56304
	s_waitcnt vmcnt(0)
	ds_write_b16 v126, v0 offset:55296
	ds_write_b16_d16_hi v126, v0 offset:55440
	ds_write_b16 v126, v1 offset:55584
	ds_write_b16_d16_hi v126, v1 offset:55728
	ds_write_b16 v126, v2 offset:55872
	ds_write_b16_d16_hi v126, v2 offset:56016
	ds_write_b16 v126, v3 offset:56160
	ds_write_b16_d16_hi v126, v3 offset:56304
	s_waitcnt lgkmcnt(0)
	s_barrier
	ds_read_b128 v[0:3], v36 offset:36864
	ds_read_b128 v[8:11], v37 offset:55296
	s_waitcnt lgkmcnt(0)
	v_mfma_f32_16x16x32_bf16 v[12:15], v[0:3], v[8:11], v[52:55]
	ds_read_b128 v[16:19], v127 offset:57600
	ds_read_b128 v[24:27], v128 offset:59904
	s_nop 0
	ds_read_b128 v[52:55], v129 offset:62208
	s_waitcnt lgkmcnt(2)
	v_mfma_f32_16x16x32_bf16 v[20:23], v[0:3], v[16:19], v[60:63]
	s_waitcnt lgkmcnt(1)
	v_mfma_f32_16x16x32_bf16 v[28:31], v[0:3], v[24:27], v[64:67]
	s_waitcnt lgkmcnt(0)
	v_mfma_f32_16x16x32_bf16 v[0:3], v[0:3], v[52:55], v[40:43]
	s_nop 2
	ds_read_b128 v[38:41], v36 offset:39168
	v_mfma_f32_16x16x32_bf16 v[4:7], v[108:111], v[120:123], v[68:71]
	s_waitcnt lgkmcnt(0)
	v_mfma_f32_16x16x32_bf16 v[60:63], v[38:41], v[8:11], v[76:79]
	v_mfma_f32_16x16x32_bf16 v[64:67], v[38:41], v[16:19], v[80:83]
	v_mfma_f32_16x16x32_bf16 v[68:71], v[38:41], v[24:27], v[84:87]
	v_mfma_f32_16x16x32_bf16 v[38:41], v[38:41], v[52:55], v[72:75]
	s_nop 2
	ds_read_b128 v[72:75], v36 offset:41472
	s_waitcnt lgkmcnt(0)
	v_mfma_f32_16x16x32_bf16 v[76:79], v[72:75], v[8:11], v[92:95]
	v_mfma_f32_16x16x32_bf16 v[80:83], v[72:75], v[16:19], v[96:99]
	v_mfma_f32_16x16x32_bf16 v[84:87], v[72:75], v[24:27], v[100:103]
	v_mfma_f32_16x16x32_bf16 v[72:75], v[72:75], v[52:55], v[88:91]
	s_nop 2
	ds_read_b128 v[88:91], v36 offset:43776
	v_mfma_f32_16x16x32_bf16 v[44:47], v[108:111], v[112:115], v[44:47]
	v_mfma_f32_16x16x32_bf16 v[48:51], v[108:111], v[104:107], v[48:51]
	v_mfma_f32_16x16x32_bf16 v[56:59], v[108:111], v[116:119], v[56:59]
	s_waitcnt lgkmcnt(0)
	v_mfma_f32_16x16x32_bf16 v[8:11], v[88:91], v[8:11], v[44:47]
	s_nop 3
	ds_read_b128 v[42:45], v36 offset:36928
	v_mfma_f32_16x16x32_bf16 v[16:19], v[88:91], v[16:19], v[48:51]
	v_mfma_f32_16x16x32_bf16 v[24:27], v[88:91], v[24:27], v[56:59]
	s_nop 1
	ds_read_b128 v[46:49], v134 offset:55296
	v_mfma_f32_16x16x32_bf16 v[4:7], v[88:91], v[52:55], v[4:7]
	ds_read_b128 v[50:53], v136 offset:57600
	ds_read_b128 v[54:57], v137 offset:59904
	ds_read_b128 v[88:91], v35 offset:62208
	s_waitcnt lgkmcnt(3)
	v_mfma_f32_16x16x32_bf16 v[12:15], v[42:45], v[46:49], v[12:15]
	v_mov_b32_e32 v35, v138
	v_lshlrev_b32_e32 v134, 1, v32
	s_waitcnt lgkmcnt(2)
	v_mfma_f32_16x16x32_bf16 v[20:23], v[42:45], v[50:53], v[20:23]
	s_waitcnt lgkmcnt(1)
	v_mfma_f32_16x16x32_bf16 v[28:31], v[42:45], v[54:57], v[28:31]
	s_waitcnt lgkmcnt(0)
	v_mfma_f32_16x16x32_bf16 v[0:3], v[42:45], v[88:91], v[0:3]
	ds_read_b128 v[42:45], v36 offset:39232
	s_waitcnt lgkmcnt(0)
	v_mfma_f32_16x16x32_bf16 v[58:61], v[42:45], v[46:49], v[60:63]
	v_mfma_f32_16x16x32_bf16 v[62:65], v[42:45], v[50:53], v[64:67]
	v_mfma_f32_16x16x32_bf16 v[66:69], v[42:45], v[54:57], v[68:71]
	v_mfma_f32_16x16x32_bf16 v[38:41], v[42:45], v[88:91], v[38:41]
	ds_read_b128 v[42:45], v36 offset:41536
	s_waitcnt lgkmcnt(0)
	v_mfma_f32_16x16x32_bf16 v[76:79], v[42:45], v[46:49], v[76:79]
	v_mfma_f32_16x16x32_bf16 v[80:83], v[42:45], v[50:53], v[80:83]
	v_mfma_f32_16x16x32_bf16 v[84:87], v[42:45], v[54:57], v[84:87]
	v_mfma_f32_16x16x32_bf16 v[42:45], v[42:45], v[88:91], v[72:75]
	s_nop 2
	ds_read_b128 v[70:73], v36 offset:43840
	s_waitcnt lgkmcnt(0)
	s_barrier
	v_mov_b32_e32 v36, v138
	v_and_b32_e32 v37, 15, v35
	v_lshrrev_b32_e32 v35, 2, v35
	v_mfma_f32_16x16x32_bf16 v[8:11], v[70:73], v[46:49], v[8:11]
	v_and_b32_e32 v35, 12, v35
	v_lshrrev_b32_e32 v46, 1, v36
	v_and_or_b32 v35, v46, s57, v35
	v_and_or_b32 v36, v36, 64, v37
	v_mul_lo_u32 v35, v35, s75
	v_lshl_add_u32 v35, v36, 2, v35
	v_mfma_f32_16x16x32_bf16 v[16:19], v[70:73], v[50:53], v[16:19]
	ds_write2_b32 v35, v12, v20 offset1:16
	ds_write2_b32 v35, v13, v21 offset0:132 offset1:148
	v_add_u32_e32 v12, 0x400, v35
	ds_write2_b32 v12, v14, v22 offset0:8 offset1:24
	ds_write2_b32 v12, v15, v23 offset0:140 offset1:156
	ds_write2_b32 v35, v28, v0 offset0:32 offset1:48
	ds_write2_b32 v35, v29, v1 offset0:164 offset1:180
	ds_write2_b32 v12, v30, v2 offset0:40 offset1:56
	ds_write2_b32 v12, v31, v3 offset0:172 offset1:188
	v_mfma_f32_16x16x32_bf16 v[24:27], v[70:73], v[54:57], v[24:27]
	v_add_u32_e32 v0, 0x2000, v35
	v_add_u32_e32 v1, 0x2400, v35
	ds_write2_b32 v0, v58, v62 offset0:64 offset1:80
	ds_write2_b32 v0, v59, v63 offset0:196 offset1:212
	v_mfma_f32_16x16x32_bf16 v[4:7], v[70:73], v[88:91], v[4:7]
	ds_write2_b32 v1, v60, v64 offset0:72 offset1:88
	ds_write2_b32 v1, v61, v65 offset0:204 offset1:220
	ds_write2_b32 v0, v66, v38 offset0:96 offset1:112
	ds_write2_b32 v0, v67, v39 offset0:228 offset1:244
	ds_write2_b32 v1, v68, v40 offset0:104 offset1:120
	ds_write2_b32 v1, v69, v41 offset0:236 offset1:252
	v_add_u32_e32 v0, 0x4000, v35
	v_add_u32_e32 v1, 0x4400, v35
	v_add_u32_e32 v2, 0x4800, v35
	ds_write2_b32 v0, v76, v80 offset0:128 offset1:144
	ds_write2_b32 v1, v77, v81 offset0:4 offset1:20
	ds_write2_b32 v1, v78, v82 offset0:136 offset1:152
	ds_write2_b32 v2, v79, v83 offset0:12 offset1:28
	ds_write2_b32 v0, v84, v42 offset0:160 offset1:176
	ds_write2_b32 v1, v85, v43 offset0:36 offset1:52
	ds_write2_b32 v1, v86, v44 offset0:168 offset1:184
	ds_write2_b32 v2, v87, v45 offset0:44 offset1:60
	v_add_u32_e32 v0, 0x6000, v35
	v_add_u32_e32 v1, 0x6400, v35
	v_add_u32_e32 v2, 0x6800, v35
	ds_write2_b32 v0, v8, v16 offset0:192 offset1:208
	ds_write2_b32 v1, v9, v17 offset0:68 offset1:84
	ds_write2_b32 v1, v10, v18 offset0:200 offset1:216
	ds_write2_b32 v2, v11, v19 offset0:76 offset1:92
	ds_write2_b32 v0, v24, v4 offset0:224 offset1:240
	ds_write2_b32 v1, v25, v5 offset0:100 offset1:116
	ds_write2_b32 v1, v26, v6 offset0:232 offset1:248
	ds_write2_b32 v2, v27, v7 offset0:108 offset1:124
	s_mov_b32 s0, 0xfffffe0
	v_add_u32_e32 v120, 0, v33
	v_ashrrev_i32_e32 v122, 4, v120
	v_lshrrev_b32_e32 v120, 3, v120
	v_and_b32_e32 v123, 15, v122
	v_add_u32_e32 v114, s1, v122
	v_and_or_b32 v110, v120, s0, v123
	v_mul_lo_u32 v120, s16, v114
	v_ashrrev_i32_e32 v121, 31, v120
	v_lshl_add_u64 v[120:121], v[120:121], 2, s[54:55]
	global_load_dwordx2 v[100:101], v[120:121], off
	v_add_u32_e32 v120, 256, v33
	v_ashrrev_i32_e32 v122, 4, v120
	v_lshrrev_b32_e32 v120, 3, v120
	v_and_b32_e32 v123, 15, v122
	v_add_u32_e32 v115, s1, v122
	v_and_or_b32 v111, v120, s0, v123
	v_mul_lo_u32 v120, s16, v115
	v_ashrrev_i32_e32 v121, 31, v120
	v_lshl_add_u64 v[120:121], v[120:121], 2, s[54:55]
	global_load_dwordx2 v[102:103], v[120:121], off
	v_add_u32_e32 v120, 512, v33
	v_ashrrev_i32_e32 v122, 4, v120
	v_lshrrev_b32_e32 v120, 3, v120
	v_and_b32_e32 v123, 15, v122
	v_add_u32_e32 v116, s1, v122
	v_and_or_b32 v112, v120, s0, v123
	v_mul_lo_u32 v120, s16, v116
	v_ashrrev_i32_e32 v121, 31, v120
	v_lshl_add_u64 v[120:121], v[120:121], 2, s[54:55]
	global_load_dwordx2 v[104:105], v[120:121], off
	v_add_u32_e32 v120, 768, v33
	v_ashrrev_i32_e32 v122, 4, v120
	v_lshrrev_b32_e32 v120, 3, v120
	v_and_b32_e32 v123, 15, v122
	v_add_u32_e32 v117, s1, v122
	v_and_or_b32 v113, v120, s0, v123
	v_mul_lo_u32 v120, s16, v117
	v_ashrrev_i32_e32 v121, 31, v120
	v_lshl_add_u64 v[120:121], v[120:121], 2, s[54:55]
	global_load_dwordx2 v[106:107], v[120:121], off
	v_lshl_add_u64 v[0:1], s[38:39], 0, v[134:135]
	s_waitcnt lgkmcnt(0)
	s_barrier
.LBB0_458:
	v_lshl_add_u32 v2, v114, 1, s17
	v_mad_u64_u32 v[14:15], s[38:39], v110, s75, v[34:35]
	v_ashrrev_i32_e32 v3, 31, v2
	v_lshlrev_b64 v[18:19], 15, v[2:3]
	ds_read_b128 v[2:5], v14
	ds_read_b128 v[6:9], v14 offset:16
	ds_read_b128 v[10:13], v14 offset:8448
	v_lshl_add_u64 v[30:31], v[0:1], 0, v[18:19]
	s_waitcnt vmcnt(3) lgkmcnt(0)
	v_pk_mul_f32 v[16:17], v[100:101], v[10:11] op_sel:[1,0]
	s_nop 0
	v_pk_fma_f32 v[20:21], v[100:101], v[2:3], v[16:17] op_sel_hi:[0,1,1]
	v_pk_mul_f32 v[16:17], v[100:101], v[12:13] op_sel:[1,0]
	v_pk_mul_f32 v[2:3], v[100:101], v[2:3] op_sel:[1,0]
	v_pk_fma_f32 v[24:25], v[100:101], v[4:5], v[16:17] op_sel_hi:[0,1,1]
	ds_read_b128 v[14:17], v14 offset:8464
	v_pk_mul_f32 v[4:5], v[100:101], v[4:5] op_sel:[1,0]
	v_pk_fma_f32 v[2:3], v[100:101], v[10:11], v[2:3] op_sel_hi:[0,1,1] neg_lo:[0,0,1] neg_hi:[0,0,1]
	v_pk_fma_f32 v[4:5], v[100:101], v[12:13], v[4:5] op_sel_hi:[0,1,1] neg_lo:[0,0,1] neg_hi:[0,0,1]
	v_cvt_pk_bf16_f32 v2, v2, v3
	s_waitcnt lgkmcnt(0)
	v_pk_mul_f32 v[26:27], v[100:101], v[14:15] op_sel:[1,0]
	v_pk_mul_f32 v[28:29], v[100:101], v[16:17] op_sel:[1,0]
	v_pk_fma_f32 v[26:27], v[100:101], v[6:7], v[26:27] op_sel_hi:[0,1,1]
	v_pk_mul_f32 v[6:7], v[100:101], v[6:7] op_sel:[1,0]
	v_pk_fma_f32 v[28:29], v[100:101], v[8:9], v[28:29] op_sel_hi:[0,1,1]
	v_pk_fma_f32 v[6:7], v[100:101], v[14:15], v[6:7] op_sel_hi:[0,1,1] neg_lo:[0,0,1] neg_hi:[0,0,1]
	v_pk_mul_f32 v[8:9], v[100:101], v[8:9] op_sel:[1,0]
	v_cvt_pk_bf16_f32 v3, v4, v5
	v_pk_fma_f32 v[8:9], v[100:101], v[16:17], v[8:9] op_sel_hi:[0,1,1] neg_lo:[0,0,1] neg_hi:[0,0,1]
	v_cvt_pk_bf16_f32 v4, v6, v7
	v_add_co_u32_e32 v6, vcc, 0x8000, v30
	v_cvt_pk_bf16_f32 v18, v20, v21
	v_cvt_pk_bf16_f32 v19, v24, v25
	v_cvt_pk_bf16_f32 v20, v26, v27
	v_cvt_pk_bf16_f32 v21, v28, v29
	v_cvt_pk_bf16_f32 v5, v8, v9
	v_addc_co_u32_e32 v7, vcc, 0, v31, vcc
	global_store_dwordx4 v[30:31], v[18:21], off
	global_store_dwordx4 v[6:7], v[2:5], off
	s_nop 1
	v_lshl_add_u32 v2, v115, 1, s17
	v_mad_u64_u32 v[14:15], s[38:39], v111, s75, v[34:35]
	v_ashrrev_i32_e32 v3, 31, v2
	v_lshlrev_b64 v[18:19], 15, v[2:3]
	ds_read_b128 v[2:5], v14
	ds_read_b128 v[6:9], v14 offset:16
	ds_read_b128 v[10:13], v14 offset:8448
	v_lshl_add_u64 v[30:31], v[0:1], 0, v[18:19]
	s_waitcnt vmcnt(4) lgkmcnt(0)
	v_pk_mul_f32 v[16:17], v[102:103], v[10:11] op_sel:[1,0]
	s_nop 0
	v_pk_fma_f32 v[20:21], v[102:103], v[2:3], v[16:17] op_sel_hi:[0,1,1]
	v_pk_mul_f32 v[16:17], v[102:103], v[12:13] op_sel:[1,0]
	v_pk_mul_f32 v[2:3], v[102:103], v[2:3] op_sel:[1,0]
	v_pk_fma_f32 v[24:25], v[102:103], v[4:5], v[16:17] op_sel_hi:[0,1,1]
	ds_read_b128 v[14:17], v14 offset:8464
	v_pk_mul_f32 v[4:5], v[102:103], v[4:5] op_sel:[1,0]
	v_pk_fma_f32 v[2:3], v[102:103], v[10:11], v[2:3] op_sel_hi:[0,1,1] neg_lo:[0,0,1] neg_hi:[0,0,1]
	v_pk_fma_f32 v[4:5], v[102:103], v[12:13], v[4:5] op_sel_hi:[0,1,1] neg_lo:[0,0,1] neg_hi:[0,0,1]
	v_cvt_pk_bf16_f32 v2, v2, v3
	s_waitcnt lgkmcnt(0)
	v_pk_mul_f32 v[26:27], v[102:103], v[14:15] op_sel:[1,0]
	v_pk_mul_f32 v[28:29], v[102:103], v[16:17] op_sel:[1,0]
	v_pk_fma_f32 v[26:27], v[102:103], v[6:7], v[26:27] op_sel_hi:[0,1,1]
	v_pk_mul_f32 v[6:7], v[102:103], v[6:7] op_sel:[1,0]
	v_pk_fma_f32 v[28:29], v[102:103], v[8:9], v[28:29] op_sel_hi:[0,1,1]
	v_pk_fma_f32 v[6:7], v[102:103], v[14:15], v[6:7] op_sel_hi:[0,1,1] neg_lo:[0,0,1] neg_hi:[0,0,1]
	v_pk_mul_f32 v[8:9], v[102:103], v[8:9] op_sel:[1,0]
	v_cvt_pk_bf16_f32 v3, v4, v5
	v_pk_fma_f32 v[8:9], v[102:103], v[16:17], v[8:9] op_sel_hi:[0,1,1] neg_lo:[0,0,1] neg_hi:[0,0,1]
	v_cvt_pk_bf16_f32 v4, v6, v7
	v_add_co_u32_e32 v6, vcc, 0x8000, v30
	v_cvt_pk_bf16_f32 v18, v20, v21
	v_cvt_pk_bf16_f32 v19, v24, v25
	v_cvt_pk_bf16_f32 v20, v26, v27
	v_cvt_pk_bf16_f32 v21, v28, v29
	v_cvt_pk_bf16_f32 v5, v8, v9
	v_addc_co_u32_e32 v7, vcc, 0, v31, vcc
	global_store_dwordx4 v[30:31], v[18:21], off
	global_store_dwordx4 v[6:7], v[2:5], off
	s_nop 1
	v_lshl_add_u32 v2, v116, 1, s17
	v_mad_u64_u32 v[14:15], s[38:39], v112, s75, v[34:35]
	v_ashrrev_i32_e32 v3, 31, v2
	v_lshlrev_b64 v[18:19], 15, v[2:3]
	ds_read_b128 v[2:5], v14
	ds_read_b128 v[6:9], v14 offset:16
	ds_read_b128 v[10:13], v14 offset:8448
	v_lshl_add_u64 v[30:31], v[0:1], 0, v[18:19]
	s_waitcnt vmcnt(5) lgkmcnt(0)
	v_pk_mul_f32 v[16:17], v[104:105], v[10:11] op_sel:[1,0]
	s_nop 0
	v_pk_fma_f32 v[20:21], v[104:105], v[2:3], v[16:17] op_sel_hi:[0,1,1]
	v_pk_mul_f32 v[16:17], v[104:105], v[12:13] op_sel:[1,0]
	v_pk_mul_f32 v[2:3], v[104:105], v[2:3] op_sel:[1,0]
	v_pk_fma_f32 v[24:25], v[104:105], v[4:5], v[16:17] op_sel_hi:[0,1,1]
	ds_read_b128 v[14:17], v14 offset:8464
	v_pk_mul_f32 v[4:5], v[104:105], v[4:5] op_sel:[1,0]
	v_pk_fma_f32 v[2:3], v[104:105], v[10:11], v[2:3] op_sel_hi:[0,1,1] neg_lo:[0,0,1] neg_hi:[0,0,1]
	v_pk_fma_f32 v[4:5], v[104:105], v[12:13], v[4:5] op_sel_hi:[0,1,1] neg_lo:[0,0,1] neg_hi:[0,0,1]
	v_cvt_pk_bf16_f32 v2, v2, v3
	s_waitcnt lgkmcnt(0)
	v_pk_mul_f32 v[26:27], v[104:105], v[14:15] op_sel:[1,0]
	v_pk_mul_f32 v[28:29], v[104:105], v[16:17] op_sel:[1,0]
	v_pk_fma_f32 v[26:27], v[104:105], v[6:7], v[26:27] op_sel_hi:[0,1,1]
	v_pk_mul_f32 v[6:7], v[104:105], v[6:7] op_sel:[1,0]
	v_pk_fma_f32 v[28:29], v[104:105], v[8:9], v[28:29] op_sel_hi:[0,1,1]
	v_pk_fma_f32 v[6:7], v[104:105], v[14:15], v[6:7] op_sel_hi:[0,1,1] neg_lo:[0,0,1] neg_hi:[0,0,1]
	v_pk_mul_f32 v[8:9], v[104:105], v[8:9] op_sel:[1,0]
	v_cvt_pk_bf16_f32 v3, v4, v5
	v_pk_fma_f32 v[8:9], v[104:105], v[16:17], v[8:9] op_sel_hi:[0,1,1] neg_lo:[0,0,1] neg_hi:[0,0,1]
	v_cvt_pk_bf16_f32 v4, v6, v7
	v_add_co_u32_e32 v6, vcc, 0x8000, v30
	v_cvt_pk_bf16_f32 v18, v20, v21
	v_cvt_pk_bf16_f32 v19, v24, v25
	v_cvt_pk_bf16_f32 v20, v26, v27
	v_cvt_pk_bf16_f32 v21, v28, v29
	v_cvt_pk_bf16_f32 v5, v8, v9
	v_addc_co_u32_e32 v7, vcc, 0, v31, vcc
	global_store_dwordx4 v[30:31], v[18:21], off
	global_store_dwordx4 v[6:7], v[2:5], off
	s_nop 1
	v_lshl_add_u32 v2, v117, 1, s17
	v_mad_u64_u32 v[14:15], s[38:39], v113, s75, v[34:35]
	v_ashrrev_i32_e32 v3, 31, v2
	v_lshlrev_b64 v[18:19], 15, v[2:3]
	ds_read_b128 v[2:5], v14
	ds_read_b128 v[6:9], v14 offset:16
	ds_read_b128 v[10:13], v14 offset:8448
	v_lshl_add_u64 v[30:31], v[0:1], 0, v[18:19]
	s_waitcnt vmcnt(6) lgkmcnt(0)
	v_pk_mul_f32 v[16:17], v[106:107], v[10:11] op_sel:[1,0]
	s_nop 0
	v_pk_fma_f32 v[20:21], v[106:107], v[2:3], v[16:17] op_sel_hi:[0,1,1]
	v_pk_mul_f32 v[16:17], v[106:107], v[12:13] op_sel:[1,0]
	v_pk_mul_f32 v[2:3], v[106:107], v[2:3] op_sel:[1,0]
	v_pk_fma_f32 v[24:25], v[106:107], v[4:5], v[16:17] op_sel_hi:[0,1,1]
	ds_read_b128 v[14:17], v14 offset:8464
	v_pk_mul_f32 v[4:5], v[106:107], v[4:5] op_sel:[1,0]
	v_pk_fma_f32 v[2:3], v[106:107], v[10:11], v[2:3] op_sel_hi:[0,1,1] neg_lo:[0,0,1] neg_hi:[0,0,1]
	v_pk_fma_f32 v[4:5], v[106:107], v[12:13], v[4:5] op_sel_hi:[0,1,1] neg_lo:[0,0,1] neg_hi:[0,0,1]
	v_cvt_pk_bf16_f32 v2, v2, v3
	s_waitcnt lgkmcnt(0)
	v_pk_mul_f32 v[26:27], v[106:107], v[14:15] op_sel:[1,0]
	v_pk_mul_f32 v[28:29], v[106:107], v[16:17] op_sel:[1,0]
	v_pk_fma_f32 v[26:27], v[106:107], v[6:7], v[26:27] op_sel_hi:[0,1,1]
	v_pk_mul_f32 v[6:7], v[106:107], v[6:7] op_sel:[1,0]
	v_pk_fma_f32 v[28:29], v[106:107], v[8:9], v[28:29] op_sel_hi:[0,1,1]
	v_pk_fma_f32 v[6:7], v[106:107], v[14:15], v[6:7] op_sel_hi:[0,1,1] neg_lo:[0,0,1] neg_hi:[0,0,1]
	v_pk_mul_f32 v[8:9], v[106:107], v[8:9] op_sel:[1,0]
	v_cvt_pk_bf16_f32 v3, v4, v5
	v_pk_fma_f32 v[8:9], v[106:107], v[16:17], v[8:9] op_sel_hi:[0,1,1] neg_lo:[0,0,1] neg_hi:[0,0,1]
	v_cvt_pk_bf16_f32 v4, v6, v7
	v_add_co_u32_e32 v6, vcc, 0x8000, v30
	v_cvt_pk_bf16_f32 v18, v20, v21
	v_cvt_pk_bf16_f32 v19, v24, v25
	v_cvt_pk_bf16_f32 v20, v26, v27
	v_cvt_pk_bf16_f32 v21, v28, v29
	v_cvt_pk_bf16_f32 v5, v8, v9
	v_addc_co_u32_e32 v7, vcc, 0, v31, vcc
	global_store_dwordx4 v[30:31], v[18:21], off
	global_store_dwordx4 v[6:7], v[2:5], off
	s_nop 1
	s_movk_i32 s13, 0x400
	s_branch .LBB0_451
